# v27 + proj K-loop: next-stage LDS-DMA issued right after the step barrier, before deferred MFMAs and first ds_reads
# baseline (speedup 1.0000x reference)
.LBB0_130:
	v_add_u32_e32 v164, v168, v189
	v_add_u32_e32 v169, v146, v189
	s_waitcnt lgkmcnt(2)
	v_mfma_f32_32x32x16_bf16 v[0:15], v[128:131], v[132:135], v[0:15]
	ds_read_b128 v[156:159], v164
	s_add_u32 s0, s0, 0x80
	s_addc_u32 s1, s1, 0
	s_add_i32 s47, s47, 1
	s_cmpk_lg_i32 s0, 0x800
	s_mov_b32 s48, s52
	v_mfma_f32_32x32x16_bf16 v[16:31], v[152:155], v[132:135], v[16:31]
	ds_read_b128 v[132:135], v164 offset:4096
	s_waitcnt lgkmcnt(4)
	v_mfma_f32_32x32x16_bf16 v[32:47], v[128:131], v[136:139], v[32:47]
	ds_read_b128 v[160:163], v164 offset:8192
	v_mfma_f32_32x32x16_bf16 v[48:63], v[152:155], v[136:139], v[48:63]
	ds_read_b128 v[136:139], v164 offset:12288
	s_waitcnt lgkmcnt(5)
	v_mfma_f32_32x32x16_bf16 v[64:79], v[128:131], v[140:143], v[64:79]
	ds_read_b128 v[164:167], v169 offset:32768
	v_mfma_f32_32x32x16_bf16 v[80:95], v[152:155], v[140:143], v[80:95]
	ds_read_b128 v[140:143], v169 offset:36864
	v_add_u32_e32 v169, v168, v190
	s_waitcnt lgkmcnt(6)
	v_mfma_f32_32x32x16_bf16 v[96:111], v[128:131], v[148:151], v[96:111]
	v_mfma_f32_32x32x16_bf16 v[112:127], v[152:155], v[148:151], v[112:127]
	s_waitcnt lgkmcnt(1)
	v_mfma_f32_32x32x16_bf16 v[0:15], v[164:167], v[156:159], v[0:15]
	ds_read_b128 v[128:131], v169
	s_waitcnt lgkmcnt(1)
	v_mfma_f32_32x32x16_bf16 v[16:31], v[140:143], v[156:159], v[16:31]
	ds_read_b128 v[148:151], v169 offset:4096
	v_mfma_f32_32x32x16_bf16 v[32:47], v[164:167], v[132:135], v[32:47]
	ds_read_b128 v[152:155], v169 offset:8192
	v_mfma_f32_32x32x16_bf16 v[48:63], v[140:143], v[132:135], v[48:63]
	ds_read_b128 v[132:135], v169 offset:12288
	v_add_u32_e32 v169, v146, v190
	v_add_u32_e32 v146, v146, v191
	v_mfma_f32_32x32x16_bf16 v[64:79], v[164:167], v[160:163], v[64:79]
	ds_read_b128 v[156:159], v169 offset:32768
	v_mfma_f32_32x32x16_bf16 v[80:95], v[140:143], v[160:163], v[80:95]
	ds_read_b128 v[160:163], v169 offset:36864
	v_mfma_f32_32x32x16_bf16 v[96:111], v[164:167], v[136:139], v[96:111]
	v_add_u32_e32 v164, v168, v191
	v_mfma_f32_32x32x16_bf16 v[112:127], v[140:143], v[136:139], v[112:127]
	s_waitcnt lgkmcnt(1)
	v_mfma_f32_32x32x16_bf16 v[0:15], v[156:159], v[128:131], v[0:15]
	ds_read_b128 v[136:139], v164
	s_waitcnt lgkmcnt(1)
	v_mfma_f32_32x32x16_bf16 v[16:31], v[160:163], v[128:131], v[16:31]
	ds_read_b128 v[128:131], v164 offset:4096
	v_mfma_f32_32x32x16_bf16 v[32:47], v[156:159], v[148:151], v[32:47]
	ds_read_b128 v[140:143], v164 offset:8192
	v_mfma_f32_32x32x16_bf16 v[48:63], v[160:163], v[148:151], v[48:63]
	ds_read_b128 v[148:151], v164 offset:12288
	v_mfma_f32_32x32x16_bf16 v[64:79], v[156:159], v[152:155], v[64:79]
	ds_read_b128 v[164:167], v146 offset:32768
	v_mfma_f32_32x32x16_bf16 v[80:95], v[160:163], v[152:155], v[80:95]
	ds_read_b128 v[152:155], v146 offset:36864
	v_mfma_f32_32x32x16_bf16 v[96:111], v[156:159], v[132:135], v[96:111]
	v_mfma_f32_32x32x16_bf16 v[112:127], v[160:163], v[132:135], v[112:127]
	s_waitcnt lgkmcnt(0)
	s_cbranch_scc0 .Lxt_L0
	s_waitcnt vmcnt(0)
	s_barrier
	s_and_b32 s4, s48, 0x10000
	v_or_b32_e32 v146, s4, v187
	v_add_u32_e32 v194, v146, v188
	v_add_u32_e32 v168, s4, v186
	v_add_u32_e32 v195, v168, v188
	s_add_i32 s52, s48, 0x10000
	s_cmp_lt_u32 s47, 15
	s_cbranch_scc0 .Ldf_L0
	s_and_b32 s4, s52, 0x10000
	s_add_i32 s53, s4, s26
	s_add_i32 s54, s53, 0x8000
	s_add_u32 s82, s0, s81
	s_addk_i32 s82, 0x80
	s_and_b32 s82, s82, 0x7ff
	s_mov_b32 s83, 0
	s_add_u32 s4, s45, s82
	s_addc_u32 s5, s46, s83
	s_mov_b32 m0, s53
	global_load_lds_dwordx4 v145, s[4:5]
	s_add_u32 s4, s43, s82
	s_addc_u32 s5, s44, s83
	s_add_i32 s55, s53, 0x400
	s_mov_b32 m0, s55
	global_load_lds_dwordx4 v185, s[4:5]
	s_add_u32 s4, s40, s82
	s_addc_u32 s5, s42, s83
	s_add_i32 s55, s53, 0x800
	s_mov_b32 m0, s55
	global_load_lds_dwordx4 v145, s[4:5]
	s_add_u32 s4, s37, s82
	s_addc_u32 s5, s39, s83
	s_add_i32 s55, s53, 0xc00
	s_mov_b32 m0, s55
	global_load_lds_dwordx4 v185, s[4:5]
	s_add_u32 s4, s35, s82
	s_addc_u32 s5, s36, s83
	s_mov_b32 m0, s54
	global_load_lds_dwordx4 v145, s[4:5]
	s_add_u32 s4, s31, s82
	s_addc_u32 s5, s34, s83
	s_add_i32 s54, s53, 0x8400
	s_mov_b32 m0, s54
	global_load_lds_dwordx4 v185, s[4:5]
	s_add_u32 s4, s29, s82
	s_addc_u32 s5, s30, s83
	s_add_i32 s54, s53, 0x8800
	s_mov_b32 m0, s54
	global_load_lds_dwordx4 v145, s[4:5]
	s_add_u32 s4, s27, s82
	s_addc_u32 s5, s28, s83
	s_add_i32 s53, s53, 0x8c00
	s_mov_b32 m0, s53
	global_load_lds_dwordx4 v185, s[4:5]
.Ldf_L0:
	ds_read_b128 v[132:135], v195
	v_mfma_f32_32x32x16_bf16 v[16:31], v[152:155], v[136:139], v[16:31]
	v_mfma_f32_32x32x16_bf16 v[48:63], v[152:155], v[128:131], v[48:63]
	v_mfma_f32_32x32x16_bf16 v[80:95], v[152:155], v[140:143], v[80:95]
	v_mfma_f32_32x32x16_bf16 v[112:127], v[152:155], v[148:151], v[112:127]
	ds_read_b128 v[152:155], v194 offset:36864
	v_mfma_f32_32x32x16_bf16 v[0:15], v[164:167], v[136:139], v[0:15]
	ds_read_b128 v[136:139], v195 offset:4096
	v_mfma_f32_32x32x16_bf16 v[32:47], v[164:167], v[128:131], v[32:47]
	ds_read_b128 v[128:131], v194 offset:32768
	v_mfma_f32_32x32x16_bf16 v[64:79], v[164:167], v[140:143], v[64:79]
	ds_read_b128 v[140:143], v195 offset:8192
	v_mfma_f32_32x32x16_bf16 v[96:111], v[164:167], v[148:151], v[96:111]
	ds_read_b128 v[148:151], v195 offset:12288
	s_branch .LBB0_130

.LBB0_725:
	v_add_u32_e32 v162, v166, v189
	v_add_u32_e32 v167, v144, v189
	s_waitcnt lgkmcnt(2)
	v_mfma_f32_32x32x16_bf16 v[0:15], v[128:131], v[132:135], v[0:15]
	ds_read_b128 v[154:157], v162
	s_add_u32 s4, s4, 0x80
	s_addc_u32 s5, s5, 0
	s_add_i32 s45, s45, 1
	s_cmpk_lg_i32 s4, 0x800
	s_mov_b32 s46, s50
	v_mfma_f32_32x32x16_bf16 v[16:31], v[150:153], v[132:135], v[16:31]
	ds_read_b128 v[132:135], v162 offset:4096
	s_waitcnt lgkmcnt(4)
	v_mfma_f32_32x32x16_bf16 v[32:47], v[128:131], v[136:139], v[32:47]
	ds_read_b128 v[158:161], v162 offset:8192
	v_mfma_f32_32x32x16_bf16 v[48:63], v[150:153], v[136:139], v[48:63]
	ds_read_b128 v[136:139], v162 offset:12288
	s_waitcnt lgkmcnt(5)
	v_mfma_f32_32x32x16_bf16 v[64:79], v[128:131], v[140:143], v[64:79]
	ds_read_b128 v[162:165], v167 offset:32768
	v_mfma_f32_32x32x16_bf16 v[80:95], v[150:153], v[140:143], v[80:95]
	ds_read_b128 v[140:143], v167 offset:36864
	v_add_u32_e32 v167, v166, v190
	s_waitcnt lgkmcnt(6)
	v_mfma_f32_32x32x16_bf16 v[96:111], v[128:131], v[146:149], v[96:111]
	v_mfma_f32_32x32x16_bf16 v[112:127], v[150:153], v[146:149], v[112:127]
	s_waitcnt lgkmcnt(1)
	v_mfma_f32_32x32x16_bf16 v[0:15], v[162:165], v[154:157], v[0:15]
	ds_read_b128 v[128:131], v167
	s_waitcnt lgkmcnt(1)
	v_mfma_f32_32x32x16_bf16 v[16:31], v[140:143], v[154:157], v[16:31]
	ds_read_b128 v[146:149], v167 offset:4096
	v_mfma_f32_32x32x16_bf16 v[32:47], v[162:165], v[132:135], v[32:47]
	ds_read_b128 v[150:153], v167 offset:8192
	v_mfma_f32_32x32x16_bf16 v[48:63], v[140:143], v[132:135], v[48:63]
	ds_read_b128 v[132:135], v167 offset:12288
	v_add_u32_e32 v167, v144, v190
	v_add_u32_e32 v144, v144, v191
	v_mfma_f32_32x32x16_bf16 v[64:79], v[162:165], v[158:161], v[64:79]
	ds_read_b128 v[154:157], v167 offset:32768
	v_mfma_f32_32x32x16_bf16 v[80:95], v[140:143], v[158:161], v[80:95]
	ds_read_b128 v[158:161], v167 offset:36864
	v_mfma_f32_32x32x16_bf16 v[96:111], v[162:165], v[136:139], v[96:111]
	v_add_u32_e32 v162, v166, v191
	v_mfma_f32_32x32x16_bf16 v[112:127], v[140:143], v[136:139], v[112:127]
	s_waitcnt lgkmcnt(1)
	v_mfma_f32_32x32x16_bf16 v[0:15], v[154:157], v[128:131], v[0:15]
	ds_read_b128 v[136:139], v162
	s_waitcnt lgkmcnt(1)
	v_mfma_f32_32x32x16_bf16 v[16:31], v[158:161], v[128:131], v[16:31]
	ds_read_b128 v[128:131], v162 offset:4096
	v_mfma_f32_32x32x16_bf16 v[32:47], v[154:157], v[146:149], v[32:47]
	ds_read_b128 v[140:143], v162 offset:8192
	v_mfma_f32_32x32x16_bf16 v[48:63], v[158:161], v[146:149], v[48:63]
	ds_read_b128 v[146:149], v162 offset:12288
	v_mfma_f32_32x32x16_bf16 v[64:79], v[154:157], v[150:153], v[64:79]
	ds_read_b128 v[162:165], v144 offset:32768
	v_mfma_f32_32x32x16_bf16 v[80:95], v[158:161], v[150:153], v[80:95]
	ds_read_b128 v[150:153], v144 offset:36864
	v_mfma_f32_32x32x16_bf16 v[96:111], v[154:157], v[132:135], v[96:111]
	v_mfma_f32_32x32x16_bf16 v[112:127], v[158:161], v[132:135], v[112:127]
	s_waitcnt lgkmcnt(0)
	s_cbranch_scc0 .Lxt_L1
	s_waitcnt vmcnt(0)
	s_barrier
	s_and_b32 s6, s46, 0x10000
	v_or_b32_e32 v144, s6, v187
	v_add_u32_e32 v194, v144, v188
	v_add_u32_e32 v166, s6, v186
	v_add_u32_e32 v195, v166, v188
	s_add_i32 s50, s46, 0x10000
	s_cmp_lt_u32 s45, 15
	s_cbranch_scc0 .Ldf_L1
	s_and_b32 s6, s50, 0x10000
	s_add_i32 s51, s6, s26
	s_add_i32 s52, s51, 0x8000
	s_add_u32 s82, s4, s81
	s_addk_i32 s82, 0x80
	s_and_b32 s82, s82, 0x7ff
	s_mov_b32 s83, 0
	s_add_u32 s6, s43, s82
	s_addc_u32 s7, s44, s83
	s_mov_b32 m0, s51
	global_load_lds_dwordx4 v177, s[6:7]
	s_add_u32 s6, s41, s82
	s_addc_u32 s7, s42, s83
	s_add_i32 s53, s51, 0x400
	s_mov_b32 m0, s53
	global_load_lds_dwordx4 v185, s[6:7]
	s_add_u32 s6, s39, s82
	s_addc_u32 s7, s40, s83
	s_add_i32 s53, s51, 0x800
	s_mov_b32 m0, s53
	global_load_lds_dwordx4 v177, s[6:7]
	s_add_u32 s6, s37, s82
	s_addc_u32 s7, s38, s83
	s_add_i32 s53, s51, 0xc00
	s_mov_b32 m0, s53
	global_load_lds_dwordx4 v185, s[6:7]
	s_add_u32 s6, s35, s82
	s_addc_u32 s7, s36, s83
	s_mov_b32 m0, s52
	global_load_lds_dwordx4 v177, s[6:7]
	s_add_u32 s6, s31, s82
	s_addc_u32 s7, s34, s83
	s_add_i32 s52, s51, 0x8400
	s_mov_b32 m0, s52
	global_load_lds_dwordx4 v185, s[6:7]
	s_add_u32 s6, s29, s82
	s_addc_u32 s7, s30, s83
	s_add_i32 s52, s51, 0x8800
	s_mov_b32 m0, s52
	global_load_lds_dwordx4 v177, s[6:7]
	s_add_u32 s6, s27, s82
	s_addc_u32 s7, s28, s83
	s_add_i32 s51, s51, 0x8c00
	s_mov_b32 m0, s51
	global_load_lds_dwordx4 v185, s[6:7]
.Ldf_L1:
	ds_read_b128 v[132:135], v195
	v_mfma_f32_32x32x16_bf16 v[16:31], v[150:153], v[136:139], v[16:31]
	v_mfma_f32_32x32x16_bf16 v[48:63], v[150:153], v[128:131], v[48:63]
	v_mfma_f32_32x32x16_bf16 v[80:95], v[150:153], v[140:143], v[80:95]
	v_mfma_f32_32x32x16_bf16 v[112:127], v[150:153], v[146:149], v[112:127]
	ds_read_b128 v[150:153], v194 offset:36864
	v_mfma_f32_32x32x16_bf16 v[0:15], v[162:165], v[136:139], v[0:15]
	ds_read_b128 v[136:139], v195 offset:4096
	v_mfma_f32_32x32x16_bf16 v[32:47], v[162:165], v[128:131], v[32:47]
	ds_read_b128 v[128:131], v194 offset:32768
	v_mfma_f32_32x32x16_bf16 v[64:79], v[162:165], v[140:143], v[64:79]
	ds_read_b128 v[140:143], v195 offset:8192
	v_mfma_f32_32x32x16_bf16 v[96:111], v[162:165], v[146:149], v[96:111]
	ds_read_b128 v[146:149], v195 offset:12288
	s_branch .LBB0_725
